# weight transposes of W_up/W_down moved from P0 into idle workgroups of GEMM tail rounds
# speedup vs baseline: 1.0129x; 1.0120x over previous
; __device__ __forceinline__ int win_dest_row(int n0) {
;     if (n0 < 5120) return n0;
;     if (n0 < 5152) return CDT + (n0 - 5120);
;     if (n0 < 7200) { const int c = n0 - 5152; return CCF + 256 * (c >> 7) + (c & 127); }
;     { const int c = n0 - 7200; return CCF + 256 * (c >> 7) + 128 + (c & 127); }
; }
; __global__ void __launch_bounds__(512, 2) mk_fwd(Args args) {
;     ...
;         for (int it = gw; it < n_items0; it += NGW) {
;             int r = it;
;             if (r < I_IN) { const int nblk = 9248 / 32, kb = r / nblk, nb = r % nblk; p0_transpose_item(w_in, DM, 9248, WinT, 64 * kb, 32 * nb, win_dest_row(32 * nb), scr, lane); continue; } r -= I_IN;
;             if (r < I_OUT) { const int nblk = DM / 32, kb = r / nblk, nb = r % nblk; p0_transpose_item(w_out, DMIX, DM, WoutT, 64 * kb, 32 * nb, 32 * nb, scr, lane); continue; } r -= I_OUT;
;             if (r < I_UP) { const int nblk = FF2 / 32, kb = r / nblk, nb = r % nblk; p0_transpose_item(w_up, DM, FF2, WupT, 64 * kb, 32 * nb, 32 * nb, scr, lane, norm_ffn_w); continue; } r -= I_UP;
;             { const int nblk = DM / 32, kb = r / nblk, nb = r % nblk; p0_transpose_item(w_down, FF, DM, WdnT, 64 * kb, 32 * nb, 32 * nb, scr, lane); }
;         }
.LBB0_18:
	s_cmp_lt_i32 s88, 1
	s_cselect_b64 s[0:1], -1, 0
	s_cmp_gt_i32 s89, 0
	s_cselect_b64 s[4:5], -1, 0
	s_and_b64 s[0:1], s[0:1], s[4:5]
	s_andn2_b64 vcc, exec, s[0:1]
	s_cbranch_vccnz .LBB0_61
	s_mov_b64 s[8:9], s[96:97]
	v_mov_b32_e32 v1, v212
	s_lshl_b32 s10, s94, 3
	v_readfirstlane_b32 s3, v1
	s_ashr_i32 s4, s3, 6
	s_lshl_b32 s3, s2, 3
	v_and_b32_e32 v3, 63, v1
	s_add_i32 s3, s4, s3
	s_cmpk_gt_i32 s3, 0x442f
	v_lshlrev_b32_e32 v0, 3, v3
	s_cbranch_scc1 .LBB0_54
	s_load_dwordx2 s[12:13], s[8:9], 0x38
	s_load_dwordx2 s[14:15], s[8:9], 0x90
	s_load_dwordx2 s[16:17], s[8:9], 0xa0
	s_load_dwordx2 s[18:19], s[8:9], 0xb8
	s_load_dwordx2 s[20:21], s[8:9], 0x98
	s_load_dwordx2 s[22:23], s[8:9], 0xd0
	v_lshrrev_b32_e32 v4, 3, v3
	v_and_b32_e32 v7, 7, v3
	v_lshlrev_b32_e32 v5, 4, v7
	v_lshlrev_b32_e32 v6, 5, v7
	s_lshl_b32 s24, s4, 14
	v_lshl_add_u32 v16, v4, 7, s24
	v_xor_b32_e32 v8, 0, v7
	v_lshl_add_u32 v8, v8, 4, v16
	v_xor_b32_e32 v9, 1, v7
	v_lshl_add_u32 v9, v9, 4, v16
	v_xor_b32_e32 v10, 2, v7
	v_lshl_add_u32 v10, v10, 4, v16
	v_xor_b32_e32 v11, 3, v7
	v_lshl_add_u32 v11, v11, 4, v16
	v_xor_b32_e32 v12, 4, v7
	v_lshl_add_u32 v12, v12, 4, v16
	v_xor_b32_e32 v13, 5, v7
	v_lshl_add_u32 v13, v13, 4, v16
	v_xor_b32_e32 v14, 6, v7
	v_lshl_add_u32 v14, v14, 4, v16
	v_xor_b32_e32 v15, 7, v7
	v_lshl_add_u32 v15, v15, 4, v16
	v_lshlrev_b32_e32 v20, 2, v7
	v_lshl_add_u32 v21, v7, 10, s24
	v_add_u32_e32 v16, 0, v4
	v_xor_b32_e32 v16, v16, v20
	v_lshl_add_u32 v16, v16, 2, v21
	v_add_u32_e32 v17, 8, v4
	v_xor_b32_e32 v17, v17, v20
	v_lshl_add_u32 v17, v17, 2, v21
	v_add_u32_e32 v18, 16, v4
	v_xor_b32_e32 v18, v18, v20
	v_lshl_add_u32 v18, v18, 2, v21
	v_add_u32_e32 v19, 24, v4
	v_xor_b32_e32 v19, v19, v20
	v_lshl_add_u32 v19, v19, 2, v21
	s_mov_b32 s11, s3
	s_waitcnt lgkmcnt(0)
	s_cmpk_lt_u32 s11, 9248
	s_cbranch_scc0 .Lp0t_pro_notin
	s_mul_hi_u32 s40, s11, 14861479
	s_mul_i32 s42, s40, 289
	s_sub_u32 s41, s11, s42
	s_mul_i32 s42, s40, 2367488
	s_lshl_b32 s43, s41, 7
	s_add_u32 s42, s42, s43
	s_add_u32 s26, s12, s42
	s_addc_u32 s27, s13, 0
	s_mov_b32 s28, 36992
	s_lshl_b32 s45, s41, 5
	s_mov_b32 s46, s45
	s_cmpk_lt_u32 s45, 5120
	s_cbranch_scc1 .Lp0t_pro_drow_done
	s_movk_i32 s46, 9216
	s_cmpk_lt_u32 s45, 5152
	s_cbranch_scc1 .Lp0t_pro_drow_done
	s_sub_u32 s47, s45, 5152
	s_movk_i32 s43, 5120
	s_cmpk_lt_u32 s45, 7200
	s_cbranch_scc1 .Lp0t_pro_drow_cf
	s_sub_u32 s47, s45, 7200
	s_movk_i32 s43, 5248

; __device__ __forceinline__ int win_dest_row(int n0) {
;     if (n0 < 5120) return n0;
;     if (n0 < 5152) return CDT + (n0 - 5120);
;     if (n0 < 7200) { const int c = n0 - 5152; return CCF + 256 * (c >> 7) + (c & 127); }
;     { const int c = n0 - 7200; return CCF + 256 * (c >> 7) + 128 + (c & 127); }
; }
; __global__ void __launch_bounds__(512, 2) mk_fwd(Args args) {
;     ...
;         for (int it = gw; it < n_items0; it += NGW) {
;             int r = it;
;             if (r < I_IN) { const int nblk = 9248 / 32, kb = r / nblk, nb = r % nblk; p0_transpose_item(w_in, DM, 9248, WinT, 64 * kb, 32 * nb, win_dest_row(32 * nb), scr, lane); continue; } r -= I_IN;
;             if (r < I_OUT) { const int nblk = DM / 32, kb = r / nblk, nb = r % nblk; p0_transpose_item(w_out, DMIX, DM, WoutT, 64 * kb, 32 * nb, 32 * nb, scr, lane); continue; } r -= I_OUT;
;             if (r < I_UP) { const int nblk = FF2 / 32, kb = r / nblk, nb = r % nblk; p0_transpose_item(w_up, DM, FF2, WupT, 64 * kb, 32 * nb, 32 * nb, scr, lane, norm_ffn_w); continue; } r -= I_UP;
;             { const int nblk = DM / 32, kb = r / nblk, nb = r % nblk; p0_transpose_item(w_down, FF, DM, WdnT, 64 * kb, 32 * nb, 32 * nb, scr, lane); }
;         }
.Lp0t_loop:
	s_cmpk_lt_u32 s11, 17456
	s_cbranch_scc0 .Lp0t_last
	s_cmpk_lt_u32 s11, 9248
	s_cbranch_scc0 .Lp0t_main_notin
	s_mul_hi_u32 s40, s11, 14861479
	s_mul_i32 s42, s40, 289
	s_sub_u32 s41, s11, s42
	s_mul_i32 s42, s40, 2367488
	s_lshl_b32 s43, s41, 7
	s_add_u32 s42, s42, s43
	s_add_u32 s26, s12, s42
	s_addc_u32 s27, s13, 0
	s_mov_b32 s28, 36992
	s_lshl_b32 s45, s41, 5
	s_mov_b32 s46, s45
	s_cmpk_lt_u32 s45, 5120
	s_cbranch_scc1 .Lp0t_main_drow_done
	s_movk_i32 s46, 9216
	s_cmpk_lt_u32 s45, 5152
	s_cbranch_scc1 .Lp0t_main_drow_done
	s_sub_u32 s47, s45, 5152
	s_movk_i32 s43, 5120
	s_cmpk_lt_u32 s45, 7200
	s_cbranch_scc1 .Lp0t_main_drow_cf
	s_sub_u32 s47, s45, 7200
	s_movk_i32 s43, 5248

; __device__ __forceinline__ unsigned pk2(float lo, float hi) { unsigned r; asm("v_cvt_pk_bf16_f32 %0, %1, %2" : "=v"(r) : "v"(lo), "v"(hi)); return r; }
; __device__ __forceinline__ void rms_row_to_bf16(const float* xrow, const float* w, bf16_t* orow, int lane) {
;     f32x4 v[8], ww[8]; float s = 0.f;
; #pragma unroll
;     for (int j = 0; j < 8; ++j) { v[j] = *(const f32x4*)(xrow + (j * 64 + lane) * 4); ww[j] = *(const f32x4*)(w + (j * 64 + lane) * 4); }
; #pragma unroll
;     for (int j = 0; j < 8; ++j) s += (v[j].x * v[j].x + v[j].y * v[j].y) + (v[j].z * v[j].z + v[j].w * v[j].w);
;     const float r = rsqrtf(wave_sum(s) * (1.f / DM) + EPS);
; #pragma unroll
;     for (int j = 0; j < 8; ++j) {
;         u32x2 o; o.x = pk2(v[j].x * r * ww[j].x, v[j].y * r * ww[j].y); o.y = pk2(v[j].z * r * ww[j].z, v[j].w * r * ww[j].w);
;         *(u32x2*)(orow + (j * 64 + lane) * 4) = o; }
; }
; __global__ void __launch_bounds__(512, 2) mk_fwd(Args args) {
;     ...
;         const int gr = (gw + NGW - (n_items0 % NGW)) % NGW;
;         for (int m = gr; m < MT; m += NGW) { const float* xr = (m < MP) ? x_prompt + (size_t)m * DM : x_sample + (size_t)(m - MP) * DM; rms_row_to_bf16(xr, norm_mix_w, XN + (size_t)m * DM, lane); }
.LBB0_54:
	s_abs_i32 s4, s10
	v_cvt_f32_u32_e32 v1, s4
	s_sub_i32 s5, 0, s4
	s_add_i32 s3, s3, s10
	v_rcp_iflag_f32_e32 v1, v1
	s_nop 0
	v_mul_f32_e32 v1, 0x4f7ffffe, v1
	v_cvt_u32_f32_e32 v1, v1
	s_nop 0
	v_readfirstlane_b32 s6, v1
	s_mul_i32 s5, s5, s6
	s_mul_hi_u32 s5, s6, s5
	s_add_i32 s6, s6, s5
	s_mul_hi_u32 s5, s6, 0x4430
	s_mul_i32 s5, s5, s4
	s_sub_i32 s5, 0x4430, s5
	s_sub_i32 s7, s5, s4
	s_cmp_ge_u32 s5, s4
	s_cselect_b32 s5, s7, s5
	s_sub_i32 s7, s5, s4
	s_cmp_ge_u32 s5, s4
	s_cselect_b32 s5, s7, s5
	s_sub_i32 s3, s3, s5
	s_ashr_i32 s5, s3, 31
	s_abs_i32 s3, s3
	s_mul_hi_u32 s6, s3, s6
	s_mul_i32 s6, s6, s4
	s_sub_i32 s3, s3, s6
	s_sub_i32 s6, s3, s4
	s_cmp_ge_u32 s3, s4
	s_cselect_b32 s3, s6, s3
	s_sub_i32 s6, s3, s4
	s_cmp_ge_u32 s3, s4
	s_cselect_b32 s3, s6, s3
	s_xor_b32 s3, s3, s5
	s_sub_i32 s4, s3, s5
	s_cmpk_gt_i32 s4, 0x21ff
	s_mov_b32 s7, 0
	s_cbranch_scc1 .LBB0_61
	s_load_dwordx2 s[12:13], s[8:9], 0x30
	s_load_dwordx2 s[14:15], s[8:9], 0xd0
	v_lshlrev_b32_e32 v2, 2, v3
	v_mov_b32_e32 v5, 0
	v_lshlrev_b32_e32 v4, 4, v3
	v_or_b32_e32 v6, 0x400, v2
	s_waitcnt lgkmcnt(0)
	v_lshl_add_u64 v[32:33], s[12:13], 0, v[4:5]
	v_lshlrev_b32_e32 v4, 2, v6
	v_or_b32_e32 v8, 0x500, v2
	v_lshl_add_u64 v[34:35], s[12:13], 0, v[4:5]
	v_lshlrev_b32_e32 v4, 2, v8
	v_or_b32_e32 v10, 0x600, v2
	v_mbcnt_lo_u32_b32 v1, -1, 0
	v_lshl_add_u64 v[36:37], s[12:13], 0, v[4:5]
	v_lshlrev_b32_e32 v4, 2, v10
	v_or_b32_e32 v12, 0x700, v2
	v_mbcnt_hi_u32_b32 v1, -1, v1
	v_lshl_add_u64 v[38:39], s[12:13], 0, v[4:5]
	v_lshlrev_b32_e32 v4, 2, v12
	v_and_b32_e32 v3, 64, v1
	v_lshl_add_u64 v[40:41], s[12:13], 0, v[4:5]
	v_add_u32_e32 v3, 64, v3
	v_xor_b32_e32 v4, 1, v1
	v_cmp_lt_i32_e32 vcc, v4, v3
	s_mov_b64 s[12:13], 0x7580000
	s_ashr_i32 s5, s4, 31
	v_cndmask_b32_e32 v4, v1, v4, vcc
	v_lshlrev_b32_e32 v44, 2, v4
	v_xor_b32_e32 v4, 2, v1
	v_cmp_lt_i32_e32 vcc, v4, v3
	s_ashr_i32 s11, s10, 31
	v_lshlrev_b32_e32 v50, 2, v2
	v_cndmask_b32_e32 v4, v1, v4, vcc
	v_lshlrev_b32_e32 v45, 2, v4
	v_xor_b32_e32 v4, 4, v1
	v_cmp_lt_i32_e32 vcc, v4, v3
	v_lshlrev_b32_e32 v51, 2, v6
	v_lshlrev_b32_e32 v52, 2, v8
	v_cndmask_b32_e32 v4, v1, v4, vcc
	v_lshlrev_b32_e32 v46, 2, v4
	v_xor_b32_e32 v4, 8, v1
	v_cmp_lt_i32_e32 vcc, v4, v3
	v_lshlrev_b32_e32 v53, 2, v10
	v_lshlrev_b32_e32 v54, 2, v12
	v_cndmask_b32_e32 v4, v1, v4, vcc
	v_lshlrev_b32_e32 v47, 2, v4
	v_xor_b32_e32 v4, 16, v1
	v_cmp_lt_i32_e32 vcc, v4, v3
	v_mov_b32_e32 v55, 0x3727c5ac
	s_mov_b32 s3, 0x800000
	v_cndmask_b32_e32 v4, v1, v4, vcc
	v_lshlrev_b32_e32 v48, 2, v4
	v_xor_b32_e32 v4, 32, v1
	v_cmp_lt_i32_e32 vcc, v4, v3
	s_nop 1
	v_cndmask_b32_e32 v1, v1, v4, vcc
	v_lshlrev_b32_e32 v49, 2, v1
	v_mov_b32_e32 v1, v5
	v_lshl_add_u64 v[0:1], s[14:15], 0, v[0:1]
	v_lshl_add_u64 v[42:43], v[0:1], 0, s[12:13]
	s_lshl_b64 s[12:13], s[4:5], 13
	s_lshl_b64 s[14:15], s[10:11], 13
	s_branch .LBB0_57

; __device__ __forceinline__ int win_dest_row(int n0) {
;     if (n0 < 5120) return n0;
;     if (n0 < 5152) return CDT + (n0 - 5120);
;     if (n0 < 7200) { const int c = n0 - 5152; return CCF + 256 * (c >> 7) + (c & 127); }
;     { const int c = n0 - 7200; return CCF + 256 * (c >> 7) + 128 + (c & 127); }
; }
; __global__ void __launch_bounds__(512, 2) mk_fwd(Args args) {
;     ...
;         for (int it = gw; it < n_items0; it += NGW) {
;             int r = it;
;             if (r < I_IN) { const int nblk = 9248 / 32, kb = r / nblk, nb = r % nblk; p0_transpose_item(w_in, DM, 9248, WinT, 64 * kb, 32 * nb, win_dest_row(32 * nb), scr, lane); continue; } r -= I_IN;
;             if (r < I_OUT) { const int nblk = DM / 32, kb = r / nblk, nb = r % nblk; p0_transpose_item(w_out, DMIX, DM, WoutT, 64 * kb, 32 * nb, 32 * nb, scr, lane); continue; } r -= I_OUT;
;             if (r < I_UP) { const int nblk = FF2 / 32, kb = r / nblk, nb = r % nblk; p0_transpose_item(w_up, DM, FF2, WupT, 64 * kb, 32 * nb, 32 * nb, scr, lane, norm_ffn_w); continue; } r -= I_UP;
;             { const int nblk = DM / 32, kb = r / nblk, nb = r % nblk; p0_transpose_item(w_down, FF, DM, WdnT, 64 * kb, 32 * nb, 32 * nb, scr, lane); }
;         }
.LBB0_153:
	v_writelane_b32 v254, s3, 0
	v_writelane_b32 v254, s4, 1
	v_writelane_b32 v254, s8, 2
	v_writelane_b32 v254, s9, 3
	v_writelane_b32 v254, s10, 4
	v_writelane_b32 v254, s11, 5
	v_writelane_b32 v254, s12, 6
	v_writelane_b32 v254, s13, 7
	v_writelane_b32 v254, s14, 8
	v_writelane_b32 v254, s15, 9
	v_writelane_b32 v254, s16, 10
	v_writelane_b32 v254, s17, 11
	v_writelane_b32 v254, s18, 12
	v_writelane_b32 v254, s19, 13
	v_writelane_b32 v254, s20, 14
	v_writelane_b32 v254, s21, 15
	v_writelane_b32 v254, s22, 16
	v_writelane_b32 v254, s23, 17
	v_writelane_b32 v254, s24, 18
	v_writelane_b32 v254, s25, 19
	v_writelane_b32 v254, s26, 20
	v_writelane_b32 v254, s27, 21
	v_writelane_b32 v254, s28, 22
	v_writelane_b32 v254, s29, 23
	v_writelane_b32 v254, s30, 24
	v_writelane_b32 v254, s31, 25
	v_writelane_b32 v254, s32, 26
	v_writelane_b32 v254, s33, 27
	v_writelane_b32 v254, s34, 28
	v_writelane_b32 v254, s35, 29
	v_writelane_b32 v254, s36, 30
	v_writelane_b32 v254, s37, 31
	v_writelane_b32 v254, s38, 32
	v_writelane_b32 v254, s39, 33
	v_writelane_b32 v254, s40, 34
	v_writelane_b32 v254, s41, 35
	v_writelane_b32 v254, s42, 36
	v_writelane_b32 v254, s43, 37
	v_writelane_b32 v254, s44, 38
	v_writelane_b32 v254, s45, 39
	v_writelane_b32 v254, s46, 40
	v_writelane_b32 v254, s47, 41
	s_cmpk_lt_u32 s2, 234
	s_cbranch_scc1 .Ltup1_skip
	s_mov_b64 s[8:9], s[96:97]
	v_and_b32_e32 v3, 63, v212
	v_readfirstlane_b32 s4, v212
	s_sub_u32 s3, s2, 234
	s_lshl_b32 s3, s3, 3
	s_lshr_b32 s4, s4, 6
	s_add_u32 s3, s3, s4
	s_add_u32 s11, s3, 17456
	s_sub_u32 s10, s94, 234
	s_lshl_b32 s10, s10, 3
	s_cmpk_lt_u32 s11, 20256
	s_cbranch_scc0 .Ltup1_skip
	s_load_dwordx2 s[12:13], s[8:9], 0x38
	s_load_dwordx2 s[14:15], s[8:9], 0x90
	s_load_dwordx2 s[16:17], s[8:9], 0xa0
	s_load_dwordx2 s[18:19], s[8:9], 0xb8
	s_load_dwordx2 s[20:21], s[8:9], 0x98
	s_load_dwordx2 s[22:23], s[8:9], 0xd0
	v_lshrrev_b32_e32 v4, 3, v3
	v_and_b32_e32 v7, 7, v3
	v_lshlrev_b32_e32 v5, 4, v7
	v_lshlrev_b32_e32 v6, 5, v7
	s_lshl_b32 s24, s4, 14
	v_lshl_add_u32 v16, v4, 7, s24
	v_xor_b32_e32 v8, 0, v7
	v_lshl_add_u32 v8, v8, 4, v16
	v_xor_b32_e32 v9, 1, v7
	v_lshl_add_u32 v9, v9, 4, v16
	v_xor_b32_e32 v10, 2, v7
	v_lshl_add_u32 v10, v10, 4, v16
	v_xor_b32_e32 v11, 3, v7
	v_lshl_add_u32 v11, v11, 4, v16
	v_xor_b32_e32 v12, 4, v7
	v_lshl_add_u32 v12, v12, 4, v16
	v_xor_b32_e32 v13, 5, v7
	v_lshl_add_u32 v13, v13, 4, v16
	v_xor_b32_e32 v14, 6, v7
	v_lshl_add_u32 v14, v14, 4, v16
	v_xor_b32_e32 v15, 7, v7
	v_lshl_add_u32 v15, v15, 4, v16
	v_lshlrev_b32_e32 v20, 2, v7
	v_lshl_add_u32 v21, v7, 10, s24
	v_add_u32_e32 v16, 0, v4
	v_xor_b32_e32 v16, v16, v20
	v_lshl_add_u32 v16, v16, 2, v21
	v_add_u32_e32 v17, 8, v4
	v_xor_b32_e32 v17, v17, v20
	v_lshl_add_u32 v17, v17, 2, v21
	v_add_u32_e32 v18, 16, v4
	v_xor_b32_e32 v18, v18, v20
	v_lshl_add_u32 v18, v18, 2, v21
	v_add_u32_e32 v19, 24, v4
	v_xor_b32_e32 v19, v19, v20
	v_lshl_add_u32 v19, v19, 2, v21
	s_waitcnt lgkmcnt(0)
	s_cmpk_lt_u32 s11, 9248
	s_cbranch_scc0 .Ltup1_pro_notin
	s_mul_hi_u32 s40, s11, 14861479
	s_mul_i32 s42, s40, 289
	s_sub_u32 s41, s11, s42
	s_mul_i32 s42, s40, 2367488
	s_lshl_b32 s43, s41, 7
	s_add_u32 s42, s42, s43
	s_add_u32 s26, s12, s42
	s_addc_u32 s27, s13, 0
	s_mov_b32 s28, 36992
	s_lshl_b32 s45, s41, 5
	s_mov_b32 s46, s45
	s_cmpk_lt_u32 s45, 5120
	s_cbranch_scc1 .Ltup1_pro_drow_done
	s_movk_i32 s46, 9216
	s_cmpk_lt_u32 s45, 5152
	s_cbranch_scc1 .Ltup1_pro_drow_done
	s_sub_u32 s47, s45, 5152
	s_movk_i32 s43, 5120
	s_cmpk_lt_u32 s45, 7200
	s_cbranch_scc1 .Ltup1_pro_drow_cf
	s_sub_u32 s47, s45, 7200
	s_movk_i32 s43, 5248

; __device__ __forceinline__ int win_dest_row(int n0) {
;     if (n0 < 5120) return n0;
;     if (n0 < 5152) return CDT + (n0 - 5120);
;     if (n0 < 7200) { const int c = n0 - 5152; return CCF + 256 * (c >> 7) + (c & 127); }
;     { const int c = n0 - 7200; return CCF + 256 * (c >> 7) + 128 + (c & 127); }
; }
; __global__ void __launch_bounds__(512, 2) mk_fwd(Args args) {
;     ...
;         for (int it = gw; it < n_items0; it += NGW) {
;             int r = it;
;             if (r < I_IN) { const int nblk = 9248 / 32, kb = r / nblk, nb = r % nblk; p0_transpose_item(w_in, DM, 9248, WinT, 64 * kb, 32 * nb, win_dest_row(32 * nb), scr, lane); continue; } r -= I_IN;
;             if (r < I_OUT) { const int nblk = DM / 32, kb = r / nblk, nb = r % nblk; p0_transpose_item(w_out, DMIX, DM, WoutT, 64 * kb, 32 * nb, 32 * nb, scr, lane); continue; } r -= I_OUT;
;             if (r < I_UP) { const int nblk = FF2 / 32, kb = r / nblk, nb = r % nblk; p0_transpose_item(w_up, DM, FF2, WupT, 64 * kb, 32 * nb, 32 * nb, scr, lane, norm_ffn_w); continue; } r -= I_UP;
;             { const int nblk = DM / 32, kb = r / nblk, nb = r % nblk; p0_transpose_item(w_down, FF, DM, WdnT, 64 * kb, 32 * nb, 32 * nb, scr, lane); }
;         }
.Ltup1_loop:
	s_cmpk_lt_u32 s11, 20256
	s_cbranch_scc0 .Ltup1_last
	s_cmpk_lt_u32 s11, 9248
	s_cbranch_scc0 .Ltup1_main_notin
	s_mul_hi_u32 s40, s11, 14861479
	s_mul_i32 s42, s40, 289
	s_sub_u32 s41, s11, s42
	s_mul_i32 s42, s40, 2367488
	s_lshl_b32 s43, s41, 7
	s_add_u32 s42, s42, s43
	s_add_u32 s26, s12, s42
	s_addc_u32 s27, s13, 0
	s_mov_b32 s28, 36992
	s_lshl_b32 s45, s41, 5
	s_mov_b32 s46, s45
	s_cmpk_lt_u32 s45, 5120
	s_cbranch_scc1 .Ltup1_main_drow_done
	s_movk_i32 s46, 9216
	s_cmpk_lt_u32 s45, 5152
	s_cbranch_scc1 .Ltup1_main_drow_done
	s_sub_u32 s47, s45, 5152
	s_movk_i32 s43, 5120
	s_cmpk_lt_u32 s45, 7200
	s_cbranch_scc1 .Ltup1_main_drow_cf
	s_sub_u32 s47, s45, 7200
	s_movk_i32 s43, 5248

; __device__ __forceinline__ unsigned xb_ld(unsigned* p)              { return __hip_atomic_load(p, __ATOMIC_RELAXED, __HIP_MEMORY_SCOPE_AGENT); }
; __device__ __forceinline__ unsigned xb_add(unsigned* p, unsigned v) { return __hip_atomic_fetch_add(p, v, __ATOMIC_RELAXED, __HIP_MEMORY_SCOPE_AGENT); }
; #define XB_SPIN(cond, bar) do { unsigned _sp = 0; while (cond) { __builtin_amdgcn_s_sleep(1); \
;     if ((++_sp & 255u) == 0u) { if (xb_ld(&(bar)[XB_TMO])) break; if (_sp > XB_SPIN_CAP) { atomicAdd(&(bar)[XB_TMO], 1u); break; } } } } while (0)
; __device__ __forceinline__ void xcd_barrier(const XcdBarrier& b) {
;     asm volatile("s_waitcnt vmcnt(0)" ::: "memory");
;     __syncthreads();
;     if (threadIdx.x == 0) {
;         unsigned* bar = b.bar;
;         __builtin_amdgcn_s_waitcnt(0);
;         unsigned nloc = b.st[0], nx = b.st[1];
;         if (nloc == 0u) { xcd_barrier_complete(bar, b.x, nloc, nx); b.st[0] = nloc; b.st[1] = nx; }
;         const unsigned old = xb_add(&bar[XB_XSUB(b.x)], 1u);
;         const unsigned gen = old / nloc;
;         if (old + 1u == (gen + 1u) * nloc) {
;             __builtin_amdgcn_fence(__ATOMIC_RELEASE, "agent");
;             asm volatile("s_waitcnt vmcnt(0)" ::: "memory");
;             const unsigned og = xb_add(&bar[XB_TOP], 1u);
;             const unsigned tg = og / nx;
;             if (og + 1u == (tg + 1u) * nx) xb_add(&bar[XB_TOPGEN], 1u);
;             else XB_SPIN(xb_ld(&bar[XB_TOPGEN]) == tg, bar);
;             __builtin_amdgcn_fence(__ATOMIC_ACQUIRE, "agent");
;             xb_add(&bar[XB_XGEN(b.x)], 1u);
;             asm volatile("s_waitcnt vmcnt(0)" ::: "memory");
;         } else {
;             XB_SPIN(xb_ld(&bar[XB_XGEN(b.x)]) == gen, bar);
;             __builtin_amdgcn_fence(__ATOMIC_ACQUIRE, "agent");
;             asm volatile("s_waitcnt vmcnt(0)" ::: "memory");
;         }
;     }
;     __syncthreads();
; }
.Ltup1_skip:
	v_readlane_b32 s3, v254, 0
	v_readlane_b32 s4, v254, 1
	v_readlane_b32 s8, v254, 2
	v_readlane_b32 s9, v254, 3
	v_readlane_b32 s10, v254, 4
	v_readlane_b32 s11, v254, 5
	v_readlane_b32 s12, v254, 6
	v_readlane_b32 s13, v254, 7
	v_readlane_b32 s14, v254, 8
	v_readlane_b32 s15, v254, 9
	v_readlane_b32 s16, v254, 10
	v_readlane_b32 s17, v254, 11
	v_readlane_b32 s18, v254, 12
	v_readlane_b32 s19, v254, 13
	v_readlane_b32 s20, v254, 14
	v_readlane_b32 s21, v254, 15
	v_readlane_b32 s22, v254, 16
	v_readlane_b32 s23, v254, 17
	v_readlane_b32 s24, v254, 18
	v_readlane_b32 s25, v254, 19
	v_readlane_b32 s26, v254, 20
	v_readlane_b32 s27, v254, 21
	v_readlane_b32 s28, v254, 22
	v_readlane_b32 s29, v254, 23
	v_readlane_b32 s30, v254, 24
	v_readlane_b32 s31, v254, 25
	v_readlane_b32 s32, v254, 26
	v_readlane_b32 s33, v254, 27
	v_readlane_b32 s34, v254, 28
	v_readlane_b32 s35, v254, 29
	v_readlane_b32 s36, v254, 30
	v_readlane_b32 s37, v254, 31
	v_readlane_b32 s38, v254, 32
	v_readlane_b32 s39, v254, 33
	v_readlane_b32 s40, v254, 34
	v_readlane_b32 s41, v254, 35
	v_readlane_b32 s42, v254, 36
	v_readlane_b32 s43, v254, 37
	v_readlane_b32 s44, v254, 38
	v_readlane_b32 s45, v254, 39
	v_readlane_b32 s46, v254, 40
	v_readlane_b32 s47, v254, 41
	s_nop 4
	s_cmp_gt_i32 s89, 2
	s_cselect_b64 s[4:5], -1, 0
	s_and_b64 s[0:1], s[0:1], s[4:5]
	s_andn2_b64 vcc, exec, s[0:1]
	s_cbranch_vccnz .LBB0_207
	s_waitcnt vmcnt(0)
	s_waitcnt vmcnt(0) lgkmcnt(0)
	s_barrier
	s_mov_b64 s[0:1], exec
	v_readlane_b32 s6, v253, 4
	v_readlane_b32 s7, v253, 5
	s_and_b64 s[6:7], s[0:1], s[6:7]
	s_mov_b64 exec, s[6:7]
	s_cbranch_execz .LBB0_206
	s_add_i32 s3, 0, 0x23fc0
	v_mov_b32_e32 v0, s3
	s_waitcnt vmcnt(0) expcnt(0) lgkmcnt(0)
	ds_read_b32 v2, v0
	s_add_i32 s3, 0, 0x23fc4
	v_mov_b32_e32 v0, s3
	ds_read_b32 v0, v0
	s_waitcnt lgkmcnt(1)
	v_cmp_ne_u32_e32 vcc, 0, v2
	s_cbranch_vccnz .LBB0_170
	v_readlane_b32 s6, v253, 0
	v_readlane_b32 s7, v253, 1
	s_load_dwordx2 s[10:11], s[6:7], 0x4
	s_add_u32 s6, s74, 0x1000
	s_addc_u32 s7, s75, 0
	s_add_u32 s8, s74, 0x1100
	s_addc_u32 s9, s75, 0
	s_waitcnt lgkmcnt(0)
	s_mul_i32 s3, s10, s94
	s_add_u32 s10, s74, 0x1200
	s_mul_i32 s3, s3, s11
	s_addc_u32 s11, s75, 0
	s_add_u32 s12, s74, 0x1300
	s_addc_u32 s13, s75, 0
	s_mov_b32 s20, 1
	v_mov_b32_e32 v16, 0
	s_branch .LBB0_158

; __device__ __forceinline__ int win_dest_row(int n0) {
;     if (n0 < 5120) return n0;
;     if (n0 < 5152) return CDT + (n0 - 5120);
;     if (n0 < 7200) { const int c = n0 - 5152; return CCF + 256 * (c >> 7) + (c & 127); }
;     { const int c = n0 - 7200; return CCF + 256 * (c >> 7) + 128 + (c & 127); }
; }
; __global__ void __launch_bounds__(512, 2) mk_fwd(Args args) {
;     ...
;         for (int it = gw; it < n_items0; it += NGW) {
;             int r = it;
;             if (r < I_IN) { const int nblk = 9248 / 32, kb = r / nblk, nb = r % nblk; p0_transpose_item(w_in, DM, 9248, WinT, 64 * kb, 32 * nb, win_dest_row(32 * nb), scr, lane); continue; } r -= I_IN;
;             if (r < I_OUT) { const int nblk = DM / 32, kb = r / nblk, nb = r % nblk; p0_transpose_item(w_out, DMIX, DM, WoutT, 64 * kb, 32 * nb, 32 * nb, scr, lane); continue; } r -= I_OUT;
;             if (r < I_UP) { const int nblk = FF2 / 32, kb = r / nblk, nb = r % nblk; p0_transpose_item(w_up, DM, FF2, WupT, 64 * kb, 32 * nb, 32 * nb, scr, lane, norm_ffn_w); continue; } r -= I_UP;
;             { const int nblk = DM / 32, kb = r / nblk, nb = r % nblk; p0_transpose_item(w_down, FF, DM, WdnT, 64 * kb, 32 * nb, 32 * nb, scr, lane); }
;         }
.LBB0_675:
	v_writelane_b32 v254, s3, 0
	v_writelane_b32 v254, s4, 1
	v_writelane_b32 v254, s8, 2
	v_writelane_b32 v254, s9, 3
	v_writelane_b32 v254, s10, 4
	v_writelane_b32 v254, s11, 5
	v_writelane_b32 v254, s12, 6
	v_writelane_b32 v254, s13, 7
	v_writelane_b32 v254, s14, 8
	v_writelane_b32 v254, s15, 9
	v_writelane_b32 v254, s16, 10
	v_writelane_b32 v254, s17, 11
	v_writelane_b32 v254, s18, 12
	v_writelane_b32 v254, s19, 13
	v_writelane_b32 v254, s20, 14
	v_writelane_b32 v254, s21, 15
	v_writelane_b32 v254, s22, 16
	v_writelane_b32 v254, s23, 17
	v_writelane_b32 v254, s24, 18
	v_writelane_b32 v254, s25, 19
	v_writelane_b32 v254, s26, 20
	v_writelane_b32 v254, s27, 21
	v_writelane_b32 v254, s28, 22
	v_writelane_b32 v254, s29, 23
	v_writelane_b32 v254, s30, 24
	v_writelane_b32 v254, s31, 25
	v_writelane_b32 v254, s32, 26
	v_writelane_b32 v254, s33, 27
	v_writelane_b32 v254, s34, 28
	v_writelane_b32 v254, s35, 29
	v_writelane_b32 v254, s36, 30
	v_writelane_b32 v254, s37, 31
	v_writelane_b32 v254, s38, 32
	v_writelane_b32 v254, s39, 33
	v_writelane_b32 v254, s40, 34
	v_writelane_b32 v254, s41, 35
	v_writelane_b32 v254, s42, 36
	v_writelane_b32 v254, s43, 37
	v_writelane_b32 v254, s44, 38
	v_writelane_b32 v254, s45, 39
	v_writelane_b32 v254, s46, 40
	v_writelane_b32 v254, s47, 41
	s_cmpk_lt_u32 s2, 128
	s_cbranch_scc1 .Ltup2_skip
	s_mov_b64 s[8:9], s[96:97]
	v_and_b32_e32 v3, 63, v212
	v_readfirstlane_b32 s4, v212
	s_sub_u32 s3, s2, 128
	s_lshl_b32 s3, s3, 3
	s_lshr_b32 s4, s4, 6
	s_add_u32 s3, s3, s4
	s_add_u32 s11, s3, 20256
	s_sub_u32 s10, s94, 128
	s_lshl_b32 s10, s10, 3
	s_cmpk_lt_u32 s11, 24352
	s_cbranch_scc0 .Ltup2_skip
	s_load_dwordx2 s[12:13], s[8:9], 0x38
	s_load_dwordx2 s[14:15], s[8:9], 0x90
	s_load_dwordx2 s[16:17], s[8:9], 0xa0
	s_load_dwordx2 s[18:19], s[8:9], 0xb8
	s_load_dwordx2 s[20:21], s[8:9], 0x98
	s_load_dwordx2 s[22:23], s[8:9], 0xd0
	v_lshrrev_b32_e32 v4, 3, v3
	v_and_b32_e32 v7, 7, v3
	v_lshlrev_b32_e32 v5, 4, v7
	v_lshlrev_b32_e32 v6, 5, v7
	s_lshl_b32 s24, s4, 14
	v_lshl_add_u32 v16, v4, 7, s24
	v_xor_b32_e32 v8, 0, v7
	v_lshl_add_u32 v8, v8, 4, v16
	v_xor_b32_e32 v9, 1, v7
	v_lshl_add_u32 v9, v9, 4, v16
	v_xor_b32_e32 v10, 2, v7
	v_lshl_add_u32 v10, v10, 4, v16
	v_xor_b32_e32 v11, 3, v7
	v_lshl_add_u32 v11, v11, 4, v16
	v_xor_b32_e32 v12, 4, v7
	v_lshl_add_u32 v12, v12, 4, v16
	v_xor_b32_e32 v13, 5, v7
	v_lshl_add_u32 v13, v13, 4, v16
	v_xor_b32_e32 v14, 6, v7
	v_lshl_add_u32 v14, v14, 4, v16
	v_xor_b32_e32 v15, 7, v7
	v_lshl_add_u32 v15, v15, 4, v16
	v_lshlrev_b32_e32 v20, 2, v7
	v_lshl_add_u32 v21, v7, 10, s24
	v_add_u32_e32 v16, 0, v4
	v_xor_b32_e32 v16, v16, v20
	v_lshl_add_u32 v16, v16, 2, v21
	v_add_u32_e32 v17, 8, v4
	v_xor_b32_e32 v17, v17, v20
	v_lshl_add_u32 v17, v17, 2, v21
	v_add_u32_e32 v18, 16, v4
	v_xor_b32_e32 v18, v18, v20
	v_lshl_add_u32 v18, v18, 2, v21
	v_add_u32_e32 v19, 24, v4
	v_xor_b32_e32 v19, v19, v20
	v_lshl_add_u32 v19, v19, 2, v21
	s_waitcnt lgkmcnt(0)
	s_cmpk_lt_u32 s11, 9248
	s_cbranch_scc0 .Ltup2_pro_notin
	s_mul_hi_u32 s40, s11, 14861479
	s_mul_i32 s42, s40, 289
	s_sub_u32 s41, s11, s42
	s_mul_i32 s42, s40, 2367488
	s_lshl_b32 s43, s41, 7
	s_add_u32 s42, s42, s43
	s_add_u32 s26, s12, s42
	s_addc_u32 s27, s13, 0
	s_mov_b32 s28, 36992
	s_lshl_b32 s45, s41, 5
	s_mov_b32 s46, s45
	s_cmpk_lt_u32 s45, 5120
	s_cbranch_scc1 .Ltup2_pro_drow_done
	s_movk_i32 s46, 9216
	s_cmpk_lt_u32 s45, 5152
	s_cbranch_scc1 .Ltup2_pro_drow_done
	s_sub_u32 s47, s45, 5152
	s_movk_i32 s43, 5120
	s_cmpk_lt_u32 s45, 7200
	s_cbranch_scc1 .Ltup2_pro_drow_cf
	s_sub_u32 s47, s45, 7200
	s_movk_i32 s43, 5248

; __device__ __forceinline__ int win_dest_row(int n0) {
;     if (n0 < 5120) return n0;
;     if (n0 < 5152) return CDT + (n0 - 5120);
;     if (n0 < 7200) { const int c = n0 - 5152; return CCF + 256 * (c >> 7) + (c & 127); }
;     { const int c = n0 - 7200; return CCF + 256 * (c >> 7) + 128 + (c & 127); }
; }
; __global__ void __launch_bounds__(512, 2) mk_fwd(Args args) {
;     ...
;         for (int it = gw; it < n_items0; it += NGW) {
;             int r = it;
;             if (r < I_IN) { const int nblk = 9248 / 32, kb = r / nblk, nb = r % nblk; p0_transpose_item(w_in, DM, 9248, WinT, 64 * kb, 32 * nb, win_dest_row(32 * nb), scr, lane); continue; } r -= I_IN;
;             if (r < I_OUT) { const int nblk = DM / 32, kb = r / nblk, nb = r % nblk; p0_transpose_item(w_out, DMIX, DM, WoutT, 64 * kb, 32 * nb, 32 * nb, scr, lane); continue; } r -= I_OUT;
;             if (r < I_UP) { const int nblk = FF2 / 32, kb = r / nblk, nb = r % nblk; p0_transpose_item(w_up, DM, FF2, WupT, 64 * kb, 32 * nb, 32 * nb, scr, lane, norm_ffn_w); continue; } r -= I_UP;
;             { const int nblk = DM / 32, kb = r / nblk, nb = r % nblk; p0_transpose_item(w_down, FF, DM, WdnT, 64 * kb, 32 * nb, 32 * nb, scr, lane); }
;         }
.Ltup2_loop:
	s_cmpk_lt_u32 s11, 24352
	s_cbranch_scc0 .Ltup2_last
	s_cmpk_lt_u32 s11, 9248
	s_cbranch_scc0 .Ltup2_main_notin
	s_mul_hi_u32 s40, s11, 14861479
	s_mul_i32 s42, s40, 289
	s_sub_u32 s41, s11, s42
	s_mul_i32 s42, s40, 2367488
	s_lshl_b32 s43, s41, 7
	s_add_u32 s42, s42, s43
	s_add_u32 s26, s12, s42
	s_addc_u32 s27, s13, 0
	s_mov_b32 s28, 36992
	s_lshl_b32 s45, s41, 5
	s_mov_b32 s46, s45
	s_cmpk_lt_u32 s45, 5120
	s_cbranch_scc1 .Ltup2_main_drow_done
	s_movk_i32 s46, 9216
	s_cmpk_lt_u32 s45, 5152
	s_cbranch_scc1 .Ltup2_main_drow_done
	s_sub_u32 s47, s45, 5152
	s_movk_i32 s43, 5120
	s_cmpk_lt_u32 s45, 7200
	s_cbranch_scc1 .Ltup2_main_drow_cf
	s_sub_u32 s47, s45, 7200
	s_movk_i32 s43, 5248

; __device__ __forceinline__ unsigned xb_ld(unsigned* p)              { return __hip_atomic_load(p, __ATOMIC_RELAXED, __HIP_MEMORY_SCOPE_AGENT); }
; __device__ __forceinline__ unsigned xb_add(unsigned* p, unsigned v) { return __hip_atomic_fetch_add(p, v, __ATOMIC_RELAXED, __HIP_MEMORY_SCOPE_AGENT); }
; #define XB_SPIN(cond, bar) do { unsigned _sp = 0; while (cond) { __builtin_amdgcn_s_sleep(1); \
;     if ((++_sp & 255u) == 0u) { if (xb_ld(&(bar)[XB_TMO])) break; if (_sp > XB_SPIN_CAP) { atomicAdd(&(bar)[XB_TMO], 1u); break; } } } } while (0)
; __device__ __forceinline__ void xcd_barrier(const XcdBarrier& b) {
;     asm volatile("s_waitcnt vmcnt(0)" ::: "memory");
;     __syncthreads();
;     if (threadIdx.x == 0) {
;         unsigned* bar = b.bar;
;         __builtin_amdgcn_s_waitcnt(0);
;         unsigned nloc = b.st[0], nx = b.st[1];
;         if (nloc == 0u) { xcd_barrier_complete(bar, b.x, nloc, nx); b.st[0] = nloc; b.st[1] = nx; }
;         const unsigned old = xb_add(&bar[XB_XSUB(b.x)], 1u);
;         const unsigned gen = old / nloc;
;         if (old + 1u == (gen + 1u) * nloc) {
;             __builtin_amdgcn_fence(__ATOMIC_RELEASE, "agent");
;             asm volatile("s_waitcnt vmcnt(0)" ::: "memory");
;             const unsigned og = xb_add(&bar[XB_TOP], 1u);
;             const unsigned tg = og / nx;
;             if (og + 1u == (tg + 1u) * nx) xb_add(&bar[XB_TOPGEN], 1u);
;             else XB_SPIN(xb_ld(&bar[XB_TOPGEN]) == tg, bar);
;             __builtin_amdgcn_fence(__ATOMIC_ACQUIRE, "agent");
;             xb_add(&bar[XB_XGEN(b.x)], 1u);
;             asm volatile("s_waitcnt vmcnt(0)" ::: "memory");
;         } else {
;             XB_SPIN(xb_ld(&bar[XB_XGEN(b.x)]) == gen, bar);
;             __builtin_amdgcn_fence(__ATOMIC_ACQUIRE, "agent");
;             asm volatile("s_waitcnt vmcnt(0)" ::: "memory");
;         }
;     }
;     __syncthreads();
; }
.Ltup2_skip:
	v_readlane_b32 s3, v254, 0
	v_readlane_b32 s4, v254, 1
	v_readlane_b32 s8, v254, 2
	v_readlane_b32 s9, v254, 3
	v_readlane_b32 s10, v254, 4
	v_readlane_b32 s11, v254, 5
	v_readlane_b32 s12, v254, 6
	v_readlane_b32 s13, v254, 7
	v_readlane_b32 s14, v254, 8
	v_readlane_b32 s15, v254, 9
	v_readlane_b32 s16, v254, 10
	v_readlane_b32 s17, v254, 11
	v_readlane_b32 s18, v254, 12
	v_readlane_b32 s19, v254, 13
	v_readlane_b32 s20, v254, 14
	v_readlane_b32 s21, v254, 15
	v_readlane_b32 s22, v254, 16
	v_readlane_b32 s23, v254, 17
	v_readlane_b32 s24, v254, 18
	v_readlane_b32 s25, v254, 19
	v_readlane_b32 s26, v254, 20
	v_readlane_b32 s27, v254, 21
	v_readlane_b32 s28, v254, 22
	v_readlane_b32 s29, v254, 23
	v_readlane_b32 s30, v254, 24
	v_readlane_b32 s31, v254, 25
	v_readlane_b32 s32, v254, 26
	v_readlane_b32 s33, v254, 27
	v_readlane_b32 s34, v254, 28
	v_readlane_b32 s35, v254, 29
	v_readlane_b32 s36, v254, 30
	v_readlane_b32 s37, v254, 31
	v_readlane_b32 s38, v254, 32
	v_readlane_b32 s39, v254, 33
	v_readlane_b32 s40, v254, 34
	v_readlane_b32 s41, v254, 35
	v_readlane_b32 s42, v254, 36
	v_readlane_b32 s43, v254, 37
	v_readlane_b32 s44, v254, 38
	v_readlane_b32 s45, v254, 39
	v_readlane_b32 s46, v254, 40
	v_readlane_b32 s47, v254, 41
	s_nop 4
	s_cmp_gt_i32 s89, 6
	s_waitcnt lgkmcnt(0)
	s_cselect_b64 s[0:1], -1, 0
	s_and_b64 s[4:5], s[6:7], s[0:1]
	s_andn2_b64 vcc, exec, s[4:5]
	s_cbranch_vccnz .LBB0_729
	s_waitcnt vmcnt(0)
	s_waitcnt vmcnt(0)
	s_barrier
	s_and_saveexec_b64 s[4:5], s[90:91]
	s_cbranch_execz .LBB0_728
	s_add_i32 s3, 0, 0x23fc0
	v_mov_b32_e32 v0, s3
	s_waitcnt vmcnt(0) expcnt(0) lgkmcnt(0)
	ds_read_b32 v2, v0
	s_add_i32 s3, 0, 0x23fc4
	v_mov_b32_e32 v0, s3
	ds_read_b32 v0, v0
	s_waitcnt lgkmcnt(1)
	v_cmp_ne_u32_e32 vcc, 0, v2
	s_cbranch_vccnz .LBB0_692
	v_readlane_b32 s6, v253, 0
	v_readlane_b32 s7, v253, 1
	s_load_dwordx2 s[10:11], s[6:7], 0x4
	s_add_u32 s6, s74, 0x1000
	s_addc_u32 s7, s75, 0
	s_add_u32 s8, s74, 0x1100
	s_addc_u32 s9, s75, 0
	s_waitcnt lgkmcnt(0)
	s_mul_i32 s3, s10, s94
	s_add_u32 s10, s74, 0x1200
	s_mul_i32 s3, s3, s11
	s_addc_u32 s11, s75, 0
	s_add_u32 s12, s74, 0x1300
	s_addc_u32 s13, s75, 0
	s_mov_b32 s20, 1
	v_mov_b32_e32 v16, 0
	s_branch .LBB0_680

; __device__ __forceinline__ int win_dest_row(int n0) {
;     if (n0 < 5120) return n0;
;     if (n0 < 5152) return CDT + (n0 - 5120);
;     if (n0 < 7200) { const int c = n0 - 5152; return CCF + 256 * (c >> 7) + (c & 127); }
;     { const int c = n0 - 7200; return CCF + 256 * (c >> 7) + 128 + (c & 127); }
; }
; __global__ void __launch_bounds__(512, 2) mk_fwd(Args args) {
;     ...
;         for (int it = gw; it < n_items0; it += NGW) {
;             int r = it;
;             if (r < I_IN) { const int nblk = 9248 / 32, kb = r / nblk, nb = r % nblk; p0_transpose_item(w_in, DM, 9248, WinT, 64 * kb, 32 * nb, win_dest_row(32 * nb), scr, lane); continue; } r -= I_IN;
;             if (r < I_OUT) { const int nblk = DM / 32, kb = r / nblk, nb = r % nblk; p0_transpose_item(w_out, DMIX, DM, WoutT, 64 * kb, 32 * nb, 32 * nb, scr, lane); continue; } r -= I_OUT;
;             if (r < I_UP) { const int nblk = FF2 / 32, kb = r / nblk, nb = r % nblk; p0_transpose_item(w_up, DM, FF2, WupT, 64 * kb, 32 * nb, 32 * nb, scr, lane, norm_ffn_w); continue; } r -= I_UP;
;             { const int nblk = DM / 32, kb = r / nblk, nb = r % nblk; p0_transpose_item(w_down, FF, DM, WdnT, 64 * kb, 32 * nb, 32 * nb, scr, lane); }
;         }
.LBB0_822:
	v_writelane_b32 v254, s3, 0
	v_writelane_b32 v254, s4, 1
	v_writelane_b32 v254, s8, 2
	v_writelane_b32 v254, s9, 3
	v_writelane_b32 v254, s10, 4
	v_writelane_b32 v254, s11, 5
	v_writelane_b32 v254, s12, 6
	v_writelane_b32 v254, s13, 7
	v_writelane_b32 v254, s14, 8
	v_writelane_b32 v254, s15, 9
	v_writelane_b32 v254, s16, 10
	v_writelane_b32 v254, s17, 11
	v_writelane_b32 v254, s18, 12
	v_writelane_b32 v254, s19, 13
	v_writelane_b32 v254, s20, 14
	v_writelane_b32 v254, s21, 15
	v_writelane_b32 v254, s22, 16
	v_writelane_b32 v254, s23, 17
	v_writelane_b32 v254, s24, 18
	v_writelane_b32 v254, s25, 19
	v_writelane_b32 v254, s26, 20
	v_writelane_b32 v254, s27, 21
	v_writelane_b32 v254, s28, 22
	v_writelane_b32 v254, s29, 23
	v_writelane_b32 v254, s30, 24
	v_writelane_b32 v254, s31, 25
	v_writelane_b32 v254, s32, 26
	v_writelane_b32 v254, s33, 27
	v_writelane_b32 v254, s34, 28
	v_writelane_b32 v254, s35, 29
	v_writelane_b32 v254, s36, 30
	v_writelane_b32 v254, s37, 31
	v_writelane_b32 v254, s38, 32
	v_writelane_b32 v254, s39, 33
	v_writelane_b32 v254, s40, 34
	v_writelane_b32 v254, s41, 35
	v_writelane_b32 v254, s42, 36
	v_writelane_b32 v254, s43, 37
	v_writelane_b32 v254, s44, 38
	v_writelane_b32 v254, s45, 39
	v_writelane_b32 v254, s46, 40
	v_writelane_b32 v254, s47, 41
	s_cmpk_lt_u32 s2, 182
	s_cbranch_scc1 .Ltdn_skip
	s_mov_b64 s[8:9], s[96:97]
	v_and_b32_e32 v3, 63, v212
	v_readfirstlane_b32 s4, v212
	s_sub_u32 s3, s2, 182
	s_lshl_b32 s3, s3, 3
	s_lshr_b32 s4, s4, 6
	s_add_u32 s3, s3, s4
	s_add_u32 s11, s3, 24352
	s_sub_u32 s10, s94, 182
	s_lshl_b32 s10, s10, 3
	s_cmpk_lt_u32 s11, 29856
	s_cbranch_scc0 .Ltdn_skip
	s_load_dwordx2 s[12:13], s[8:9], 0x38
	s_load_dwordx2 s[14:15], s[8:9], 0x90
	s_load_dwordx2 s[16:17], s[8:9], 0xa0
	s_load_dwordx2 s[18:19], s[8:9], 0xb8
	s_load_dwordx2 s[20:21], s[8:9], 0x98
	s_load_dwordx2 s[22:23], s[8:9], 0xd0
	v_lshrrev_b32_e32 v4, 3, v3
	v_and_b32_e32 v7, 7, v3
	v_lshlrev_b32_e32 v5, 4, v7
	v_lshlrev_b32_e32 v6, 5, v7
	s_lshl_b32 s24, s4, 14
	v_lshl_add_u32 v16, v4, 7, s24
	v_xor_b32_e32 v8, 0, v7
	v_lshl_add_u32 v8, v8, 4, v16
	v_xor_b32_e32 v9, 1, v7
	v_lshl_add_u32 v9, v9, 4, v16
	v_xor_b32_e32 v10, 2, v7
	v_lshl_add_u32 v10, v10, 4, v16
	v_xor_b32_e32 v11, 3, v7
	v_lshl_add_u32 v11, v11, 4, v16
	v_xor_b32_e32 v12, 4, v7
	v_lshl_add_u32 v12, v12, 4, v16
	v_xor_b32_e32 v13, 5, v7
	v_lshl_add_u32 v13, v13, 4, v16
	v_xor_b32_e32 v14, 6, v7
	v_lshl_add_u32 v14, v14, 4, v16
	v_xor_b32_e32 v15, 7, v7
	v_lshl_add_u32 v15, v15, 4, v16
	v_lshlrev_b32_e32 v20, 2, v7
	v_lshl_add_u32 v21, v7, 10, s24
	v_add_u32_e32 v16, 0, v4
	v_xor_b32_e32 v16, v16, v20
	v_lshl_add_u32 v16, v16, 2, v21
	v_add_u32_e32 v17, 8, v4
	v_xor_b32_e32 v17, v17, v20
	v_lshl_add_u32 v17, v17, 2, v21
	v_add_u32_e32 v18, 16, v4
	v_xor_b32_e32 v18, v18, v20
	v_lshl_add_u32 v18, v18, 2, v21
	v_add_u32_e32 v19, 24, v4
	v_xor_b32_e32 v19, v19, v20
	v_lshl_add_u32 v19, v19, 2, v21
	s_waitcnt lgkmcnt(0)
	s_cmpk_lt_u32 s11, 9248
	s_cbranch_scc0 .Ltdn_pro_notin
	s_mul_hi_u32 s40, s11, 14861479
	s_mul_i32 s42, s40, 289
	s_sub_u32 s41, s11, s42
	s_mul_i32 s42, s40, 2367488
	s_lshl_b32 s43, s41, 7
	s_add_u32 s42, s42, s43
	s_add_u32 s26, s12, s42
	s_addc_u32 s27, s13, 0
	s_mov_b32 s28, 36992
	s_lshl_b32 s45, s41, 5
	s_mov_b32 s46, s45
	s_cmpk_lt_u32 s45, 5120
	s_cbranch_scc1 .Ltdn_pro_drow_done
	s_movk_i32 s46, 9216
	s_cmpk_lt_u32 s45, 5152
	s_cbranch_scc1 .Ltdn_pro_drow_done
	s_sub_u32 s47, s45, 5152
	s_movk_i32 s43, 5120
	s_cmpk_lt_u32 s45, 7200
	s_cbranch_scc1 .Ltdn_pro_drow_cf
	s_sub_u32 s47, s45, 7200
	s_movk_i32 s43, 5248

; __device__ __forceinline__ unsigned xb_ld(unsigned* p)              { return __hip_atomic_load(p, __ATOMIC_RELAXED, __HIP_MEMORY_SCOPE_AGENT); }
; __device__ __forceinline__ unsigned xb_add(unsigned* p, unsigned v) { return __hip_atomic_fetch_add(p, v, __ATOMIC_RELAXED, __HIP_MEMORY_SCOPE_AGENT); }
; #define XB_SPIN(cond, bar) do { unsigned _sp = 0; while (cond) { __builtin_amdgcn_s_sleep(1); \
;     if ((++_sp & 255u) == 0u) { if (xb_ld(&(bar)[XB_TMO])) break; if (_sp > XB_SPIN_CAP) { atomicAdd(&(bar)[XB_TMO], 1u); break; } } } } while (0)
; __device__ __forceinline__ void xcd_barrier(const XcdBarrier& b) {
;     asm volatile("s_waitcnt vmcnt(0)" ::: "memory");
;     __syncthreads();
;     if (threadIdx.x == 0) {
;         unsigned* bar = b.bar;
;         __builtin_amdgcn_s_waitcnt(0);
;         unsigned nloc = b.st[0], nx = b.st[1];
;         if (nloc == 0u) { xcd_barrier_complete(bar, b.x, nloc, nx); b.st[0] = nloc; b.st[1] = nx; }
;         const unsigned old = xb_add(&bar[XB_XSUB(b.x)], 1u);
;         const unsigned gen = old / nloc;
;         if (old + 1u == (gen + 1u) * nloc) {
;             __builtin_amdgcn_fence(__ATOMIC_RELEASE, "agent");
;             asm volatile("s_waitcnt vmcnt(0)" ::: "memory");
;             const unsigned og = xb_add(&bar[XB_TOP], 1u);
;             const unsigned tg = og / nx;
;             if (og + 1u == (tg + 1u) * nx) xb_add(&bar[XB_TOPGEN], 1u);
;             else XB_SPIN(xb_ld(&bar[XB_TOPGEN]) == tg, bar);
;             __builtin_amdgcn_fence(__ATOMIC_ACQUIRE, "agent");
;             xb_add(&bar[XB_XGEN(b.x)], 1u);
;             asm volatile("s_waitcnt vmcnt(0)" ::: "memory");
;         } else {
;             XB_SPIN(xb_ld(&bar[XB_XGEN(b.x)]) == gen, bar);
;             __builtin_amdgcn_fence(__ATOMIC_ACQUIRE, "agent");
;             asm volatile("s_waitcnt vmcnt(0)" ::: "memory");
;         }
;     }
;     __syncthreads();
; }
.Ltdn_skip:
	v_readlane_b32 s3, v254, 0
	v_readlane_b32 s4, v254, 1
	v_readlane_b32 s8, v254, 2
	v_readlane_b32 s9, v254, 3
	v_readlane_b32 s10, v254, 4
	v_readlane_b32 s11, v254, 5
	v_readlane_b32 s12, v254, 6
	v_readlane_b32 s13, v254, 7
	v_readlane_b32 s14, v254, 8
	v_readlane_b32 s15, v254, 9
	v_readlane_b32 s16, v254, 10
	v_readlane_b32 s17, v254, 11
	v_readlane_b32 s18, v254, 12
	v_readlane_b32 s19, v254, 13
	v_readlane_b32 s20, v254, 14
	v_readlane_b32 s21, v254, 15
	v_readlane_b32 s22, v254, 16
	v_readlane_b32 s23, v254, 17
	v_readlane_b32 s24, v254, 18
	v_readlane_b32 s25, v254, 19
	v_readlane_b32 s26, v254, 20
	v_readlane_b32 s27, v254, 21
	v_readlane_b32 s28, v254, 22
	v_readlane_b32 s29, v254, 23
	v_readlane_b32 s30, v254, 24
	v_readlane_b32 s31, v254, 25
	v_readlane_b32 s32, v254, 26
	v_readlane_b32 s33, v254, 27
	v_readlane_b32 s34, v254, 28
	v_readlane_b32 s35, v254, 29
	v_readlane_b32 s36, v254, 30
	v_readlane_b32 s37, v254, 31
	v_readlane_b32 s38, v254, 32
	v_readlane_b32 s39, v254, 33
	v_readlane_b32 s40, v254, 34
	v_readlane_b32 s41, v254, 35
	v_readlane_b32 s42, v254, 36
	v_readlane_b32 s43, v254, 37
	v_readlane_b32 s44, v254, 38
	v_readlane_b32 s45, v254, 39
	v_readlane_b32 s46, v254, 40
	v_readlane_b32 s47, v254, 41
	s_nop 4
	s_cmp_gt_i32 s89, 8
	s_waitcnt lgkmcnt(0)
	s_cselect_b64 s[4:5], -1, 0
	s_and_b64 s[0:1], s[0:1], s[4:5]
	s_andn2_b64 vcc, exec, s[0:1]
	s_cbranch_vccnz .LBB0_876
	s_waitcnt vmcnt(0)
	s_waitcnt vmcnt(0)
	s_barrier
	s_and_saveexec_b64 s[0:1], s[90:91]
	s_cbranch_execz .LBB0_875
	s_add_i32 s3, 0, 0x23fc0
	v_mov_b32_e32 v0, s3
	s_waitcnt vmcnt(0) expcnt(0) lgkmcnt(0)
	ds_read_b32 v2, v0
	s_add_i32 s3, 0, 0x23fc4
	v_mov_b32_e32 v0, s3
	ds_read_b32 v0, v0
	s_waitcnt lgkmcnt(1)
	v_cmp_ne_u32_e32 vcc, 0, v2
	s_cbranch_vccnz .LBB0_839
	v_readlane_b32 s6, v253, 0
	v_readlane_b32 s7, v253, 1
	s_load_dwordx2 s[10:11], s[6:7], 0x4
	s_add_u32 s6, s74, 0x1000
	s_addc_u32 s7, s75, 0
	s_add_u32 s8, s74, 0x1100
	s_addc_u32 s9, s75, 0
	s_waitcnt lgkmcnt(0)
	s_mul_i32 s3, s10, s94
	s_add_u32 s10, s74, 0x1200
	s_mul_i32 s3, s3, s11
	s_addc_u32 s11, s75, 0
	s_add_u32 s12, s74, 0x1300
	s_addc_u32 s13, s75, 0
	s_mov_b32 s20, 1
	v_mov_b32_e32 v16, 0
	s_branch .LBB0_827

; __global__ void __launch_bounds__(512, 2) mk_fwd(Args args) {
	.amdhsa_kernel _Z6mk_fwd4Args
		.amdhsa_group_segment_fixed_size 0
		.amdhsa_private_segment_fixed_size 0
		.amdhsa_kernarg_size 488
		.amdhsa_user_sgpr_count 2
		.amdhsa_user_sgpr_dispatch_ptr 0
		.amdhsa_user_sgpr_queue_ptr 0
		.amdhsa_user_sgpr_kernarg_segment_ptr 1
		.amdhsa_user_sgpr_dispatch_id 0
		.amdhsa_user_sgpr_kernarg_preload_length 0
		.amdhsa_user_sgpr_kernarg_preload_offset 0
		.amdhsa_user_sgpr_private_segment_size 0
		.amdhsa_uses_dynamic_stack 0
		.amdhsa_enable_private_segment 0
		.amdhsa_system_sgpr_workgroup_id_x 1
		.amdhsa_system_sgpr_workgroup_id_y 0
		.amdhsa_system_sgpr_workgroup_id_z 0
		.amdhsa_system_sgpr_workgroup_info 0
		.amdhsa_system_vgpr_workitem_id 2
		.amdhsa_next_free_vgpr 256
		.amdhsa_next_free_sgpr 98
		.amdhsa_accum_offset 256
		.amdhsa_reserve_vcc 1
		.amdhsa_float_round_mode_32 0
		.amdhsa_float_round_mode_16_64 0
		.amdhsa_float_denorm_mode_32 3
		.amdhsa_float_denorm_mode_16_64 3
		.amdhsa_dx10_clamp 1
		.amdhsa_ieee_mode 1
		.amdhsa_fp16_overflow 0
		.amdhsa_tg_split 0
		.amdhsa_exception_fp_ieee_invalid_op 0
		.amdhsa_exception_fp_denorm_src 0
		.amdhsa_exception_fp_ieee_div_zero 0
		.amdhsa_exception_fp_ieee_overflow 0
		.amdhsa_exception_fp_ieee_underflow 0
		.amdhsa_exception_fp_ieee_inexact 0
		.amdhsa_exception_int_div_zero 0
	.end_amdhsa_kernel

; __device__ __forceinline__ KArgs ka_get() { KArgs p = (KArgs)__builtin_amdgcn_kernarg_segment_ptr(); asm volatile("" : "+s"(p)); return p; }
; __global__ void __launch_bounds__(512, 2) mk_fwd(Args args) {
amdhsa.kernels:
  - .agpr_count:     0
    .args:
      - .offset:         0
        .size:           232
        .value_kind:     by_value
      - .offset:         232
        .size:           4
        .value_kind:     hidden_block_count_x
      - .offset:         236
        .size:           4
        .value_kind:     hidden_block_count_y
      - .offset:         240
        .size:           4
        .value_kind:     hidden_block_count_z
      - .offset:         244
        .size:           2
        .value_kind:     hidden_group_size_x
      - .offset:         246
        .size:           2
        .value_kind:     hidden_group_size_y
      - .offset:         248
        .size:           2
        .value_kind:     hidden_group_size_z
      - .offset:         250
        .size:           2
        .value_kind:     hidden_remainder_x
      - .offset:         252
        .size:           2
        .value_kind:     hidden_remainder_y
      - .offset:         254
        .size:           2
        .value_kind:     hidden_remainder_z
      - .offset:         272
        .size:           8
        .value_kind:     hidden_global_offset_x
      - .offset:         280
        .size:           8
        .value_kind:     hidden_global_offset_y
      - .offset:         288
        .size:           8
        .value_kind:     hidden_global_offset_z
      - .offset:         296
        .size:           2
        .value_kind:     hidden_grid_dims
      - .offset:         320
        .size:           8
        .value_kind:     hidden_multigrid_sync_arg
      - .offset:         352
        .size:           4
        .value_kind:     hidden_dynamic_lds_size
    .group_segment_fixed_size: 0
    .kernarg_segment_align: 8
    .kernarg_segment_size: 488
    .language:       OpenCL C
    .language_version:
      - 2
      - 0
    .max_flat_workgroup_size: 512
    .name:           _Z6mk_fwd4Args
    .private_segment_fixed_size: 0
    .sgpr_count:     104
    .sgpr_spill_count: 66
    .symbol:         _Z6mk_fwd4Args.kd
    .uniform_work_group_size: 1
    .uses_dynamic_stack: false
    .vgpr_count:     256
    .vgpr_spill_count: 0
    .wavefront_size: 64
